# S5 output pass: packed f32 scan ops split into scalar VALU ops, hazard nops and dead halves removed
# speedup vs baseline: 1.0269x; 1.0069x over previous
.LBB0_644:
	v_cndmask_b32_e64 v127, v55, v51, s[8:9]
	v_cndmask_b32_e64 v126, v54, v50, s[8:9]
	v_cndmask_b32_e64 v125, v53, v49, s[8:9]
	v_cndmask_b32_e64 v124, v52, v48, s[8:9]
	s_mov_b64 s[14:15], -1
	s_andn2_b64 vcc, exec, s[10:11]
	v_mfma_f32_32x32x16_bf16 v[32:47], v[124:127], v[56:59], 0
	s_nop 11
	v_cvt_pk_bf16_f32 v32, v32, v33
	v_cvt_pk_bf16_f32 v33, v34, v35
	v_cvt_pk_bf16_f32 v34, v36, v37
	v_cvt_pk_bf16_f32 v35, v38, v39
	v_cvt_pk_bf16_f32 v36, v40, v41
	v_cvt_pk_bf16_f32 v37, v42, v43
	v_cvt_pk_bf16_f32 v38, v44, v45
	v_cvt_pk_bf16_f32 v39, v46, v47
	ds_write2_b64 v205, v[32:33], v[34:35] offset1:2
	ds_write2_b64 v205, v[36:37], v[38:39] offset0:4 offset1:6
	v_mfma_f32_32x32x16_bf16 v[32:47], v[124:127], v[60:63], 0
	s_nop 11
	v_cvt_pk_bf16_f32 v32, v32, v33
	v_cvt_pk_bf16_f32 v33, v34, v35
	v_cvt_pk_bf16_f32 v34, v36, v37
	v_cvt_pk_bf16_f32 v35, v38, v39
	v_add_u32_e32 v36, 0x800, v205
	ds_write2_b64 v36, v[32:33], v[34:35] offset0:64 offset1:66
	v_cvt_pk_bf16_f32 v32, v40, v41
	v_cvt_pk_bf16_f32 v33, v42, v43
	v_cvt_pk_bf16_f32 v34, v44, v45
	v_cvt_pk_bf16_f32 v35, v46, v47
	ds_write2_b64 v36, v[32:33], v[34:35] offset0:68 offset1:70
	v_mfma_f32_32x32x16_bf16 v[32:47], v[124:127], v[64:67], 0
	s_nop 11
	v_cvt_pk_bf16_f32 v32, v32, v33
	v_cvt_pk_bf16_f32 v33, v34, v35
	v_cvt_pk_bf16_f32 v34, v36, v37
	v_cvt_pk_bf16_f32 v35, v38, v39
	v_add_u32_e32 v36, 0x1000, v205
	ds_write2_b64 v36, v[32:33], v[34:35] offset0:128 offset1:130
	v_cvt_pk_bf16_f32 v32, v40, v41
	v_cvt_pk_bf16_f32 v33, v42, v43
	v_cvt_pk_bf16_f32 v34, v44, v45
	v_cvt_pk_bf16_f32 v35, v46, v47
	ds_write2_b64 v36, v[32:33], v[34:35] offset0:132 offset1:134
	v_mfma_f32_32x32x16_bf16 v[32:47], v[124:127], v[68:71], 0
	s_nop 11
	v_cvt_pk_bf16_f32 v32, v32, v33
	v_cvt_pk_bf16_f32 v33, v34, v35
	v_cvt_pk_bf16_f32 v34, v36, v37
	v_cvt_pk_bf16_f32 v35, v38, v39
	v_add_u32_e32 v36, 0x1800, v205
	ds_write2_b64 v36, v[32:33], v[34:35] offset0:192 offset1:194
	v_cvt_pk_bf16_f32 v32, v40, v41
	v_cvt_pk_bf16_f32 v33, v42, v43
	v_cvt_pk_bf16_f32 v34, v44, v45
	v_cvt_pk_bf16_f32 v35, v46, v47
	ds_write2_b64 v36, v[32:33], v[34:35] offset0:196 offset1:198
	s_waitcnt lgkmcnt(0)
	v_add_u32_e32 v40, s20, v199
	ds_read_b128 v[32:35], v40
	ds_read_b128 v[36:39], v40 offset:5120
	ds_read_b128 v[138:141], v40 offset:16
	ds_read_b128 v[142:145], v40 offset:5136
	s_waitcnt lgkmcnt(3)
	v_lshlrev_b32_e32 v163, 16, v32
	v_and_b32_e32 v157, 0xffff0000, v32
	v_lshlrev_b32_e32 v151, 16, v33
	v_and_b32_e32 v137, 0xffff0000, v33
	v_mul_f32_e64 v32, v118, v122
	v_mul_f32_e64 v33, v119, v122
	s_waitcnt lgkmcnt(2)
	v_lshlrev_b32_e32 v162, 16, v36
	v_fma_f32 v182, v120, v112, -v32
	v_fma_f32 v183, v121, v112, -v33
	v_fma_f32 v178, v120, v112, v32
	v_cndmask_b32_e64 v32, 0, 1, s[10:11]
	v_and_b32_e32 v156, 0xffff0000, v36
	v_lshlrev_b32_e32 v150, 16, v37
	v_and_b32_e32 v136, 0xffff0000, v37
	v_lshlrev_b32_e32 v133, 16, v34
	v_lshlrev_b32_e32 v132, 16, v38
	v_and_b32_e32 v131, 0xffff0000, v34
	v_and_b32_e32 v130, 0xffff0000, v38
	v_lshlrev_b32_e32 v129, 16, v35
	v_lshlrev_b32_e32 v128, 16, v39
	v_and_b32_e32 v127, 0xffff0000, v35
	v_and_b32_e32 v126, 0xffff0000, v39
	s_waitcnt lgkmcnt(1)
	v_lshlrev_b32_e32 v125, 16, v138
	s_waitcnt lgkmcnt(0)
	v_lshlrev_b32_e32 v124, 16, v142
	v_and_b32_e32 v47, 0xffff0000, v138
	v_and_b32_e32 v46, 0xffff0000, v142
	v_lshlrev_b32_e32 v45, 16, v139
	v_lshlrev_b32_e32 v44, 16, v143
	v_and_b32_e32 v43, 0xffff0000, v139
	v_and_b32_e32 v42, 0xffff0000, v143
	v_lshlrev_b32_e32 v41, 16, v140
	v_lshlrev_b32_e32 v40, 16, v144
	v_and_b32_e32 v39, 0xffff0000, v140
	v_and_b32_e32 v38, 0xffff0000, v144
	v_lshlrev_b32_e32 v37, 16, v141
	v_lshlrev_b32_e32 v36, 16, v145
	v_and_b32_e32 v35, 0xffff0000, v145
	v_and_b32_e32 v34, 0xffff0000, v141
	v_cmp_ne_u32_e64 s[4:5], 1, v32
	v_mov_b32_e32 v179, v183
	s_cbranch_vccnz .LBB0_646
	v_add_f32_e64 v168, v178, v35
	v_add_f32_e64 v169, v179, v34
	v_add_f32_e64 v176, v183, v34
	v_add_f32_e64 v177, v182, v35
	v_mul_f32_e64 v32, v118, v168
	v_mul_f32_e64 v33, v119, v168
	s_mov_b64 s[14:15], 0
	v_fma_f32 v122, v120, v176, v32
	v_fma_f32 v33, v121, v176, -v33
	v_mov_b32_e32 v123, v33
	v_add_f32_e64 v138, v122, v36
	v_add_f32_e64 v139, v123, v37
	v_mul_f32_e32 v32, v118, v139
	v_fma_f32 v33, -v119, v138, v32
	v_mul_f32_e32 v32, v119, v139
	v_fma_f32 v122, v118, v138, v32
	v_mov_b32_e32 v123, v33
	v_add_f32_e64 v140, v122, v38
	v_add_f32_e64 v141, v123, v39
	v_mul_f32_e64 v32, v118, v140
	v_mul_f32_e64 v33, v119, v140
	v_fma_f32 v122, v120, v141, v32
	v_fma_f32 v33, v121, v141, -v33
	v_mov_b32_e32 v123, v33
	v_add_f32_e64 v144, v122, v40
	v_add_f32_e64 v145, v123, v41
	v_mul_f32_e32 v32, v118, v145
	v_fma_f32 v33, -v119, v144, v32
	v_mul_f32_e32 v32, v119, v145
	v_fma_f32 v122, v118, v144, v32
	v_mov_b32_e32 v123, v33
	v_add_f32_e64 v134, v122, v42
	v_add_f32_e64 v135, v123, v43
	v_mul_f32_e64 v32, v118, v134
	v_mul_f32_e64 v33, v119, v134
	v_fma_f32 v122, v120, v135, v32
	v_fma_f32 v33, v121, v135, -v33
	v_mov_b32_e32 v123, v33
	v_add_f32_e64 v146, v122, v44
	v_add_f32_e64 v147, v123, v45
	v_mul_f32_e32 v32, v118, v147
	v_fma_f32 v33, -v119, v146, v32
	v_mul_f32_e32 v32, v119, v147
	v_fma_f32 v122, v118, v146, v32
	v_mov_b32_e32 v123, v33
	v_add_f32_e64 v122, v122, v46
	v_add_f32_e64 v123, v123, v47
	v_mul_f32_e64 v32, v118, v122
	v_mul_f32_e64 v33, v119, v122
	v_fma_f32 v142, v120, v123, v32
	v_fma_f32 v33, v121, v123, -v33
	v_mov_b32_e32 v143, v33
	v_add_f32_e64 v148, v142, v124
	v_add_f32_e64 v149, v143, v125
	v_mul_f32_e32 v32, v118, v149
	v_fma_f32 v33, -v119, v148, v32
	v_mul_f32_e32 v32, v119, v149
	v_fma_f32 v142, v118, v148, v32
	v_mov_b32_e32 v143, v33
	v_add_f32_e64 v152, v142, v126
	v_add_f32_e64 v153, v143, v127
	v_mul_f32_e32 v32, v118, v153
	v_fma_f32 v33, -v119, v152, v32
	v_mul_f32_e32 v32, v119, v153
	v_fma_f32 v142, v118, v152, v32
	v_mov_b32_e32 v143, v33
	v_add_f32_e64 v158, v142, v128
	v_add_f32_e64 v159, v143, v129
	v_mul_f32_e32 v32, v118, v159
	v_fma_f32 v33, -v119, v158, v32
	v_mul_f32_e32 v32, v119, v159
	v_fma_f32 v142, v118, v158, v32
	v_mov_b32_e32 v143, v33
	v_add_f32_e64 v142, v142, v130
	v_add_f32_e64 v143, v143, v131
	v_mul_f32_e32 v32, v118, v143
	v_fma_f32 v33, -v119, v142, v32
	v_mul_f32_e32 v32, v119, v143
	v_fma_f32 v154, v118, v142, v32
	v_mov_b32_e32 v155, v33
	v_add_f32_e64 v164, v154, v132
	v_add_f32_e64 v165, v155, v133
	v_mul_f32_e32 v32, v118, v165
	v_fma_f32 v33, -v119, v164, v32
	v_mul_f32_e32 v32, v119, v165
	v_fma_f32 v154, v118, v164, v32
	v_mov_b32_e32 v155, v33
	v_add_f32_e64 v154, v154, v136
	v_add_f32_e64 v155, v155, v137
	v_mul_f32_e32 v32, v118, v155
	v_fma_f32 v33, -v119, v154, v32
	v_mul_f32_e32 v32, v119, v155
	v_fma_f32 v160, v118, v154, v32
	v_mov_b32_e32 v161, v33
	v_add_f32_e64 v166, v160, v150
	v_add_f32_e64 v167, v161, v151
	v_mul_f32_e32 v32, v118, v167
	v_fma_f32 v33, -v119, v166, v32
	v_mul_f32_e32 v32, v119, v167
	v_fma_f32 v160, v118, v166, v32
	v_mov_b32_e32 v161, v33
	v_add_f32_e64 v160, v160, v156
	v_add_f32_e64 v161, v161, v157
	v_mul_f32_e32 v32, v118, v161
	v_fma_f32 v33, -v119, v160, v32
	v_mul_f32_e32 v32, v119, v161
	v_fma_f32 v172, v118, v160, v32
	v_mov_b32_e32 v173, v33
	v_add_f32_e64 v32, v172, v162
	v_add_f32_e64 v33, v173, v163
	v_mov_b32_e32 v112, v32
	v_mov_b32_e32 v180, v33
.LBB0_646:
	s_andn2_b64 vcc, exec, s[14:15]
	s_cbranch_vccnz .LBB0_648
	v_add_f32_e64 v32, v178, v162
	v_add_f32_e64 v33, v179, v163
	v_mul_f32_e32 v112, v118, v33
	v_fma_f32 v123, -v119, v32, v112
	v_mul_f32_e32 v112, v119, v33
	v_fma_f32 v134, v118, v32, v112
	v_mov_b32_e32 v135, v123
	v_add_f32_e64 v160, v134, v156
	v_add_f32_e64 v161, v135, v157
	v_mul_f32_e64 v122, v118, v160
	v_mul_f32_e64 v123, v119, v160
	v_fma_f32 v134, v120, v161, v122
	v_fma_f32 v123, v121, v161, -v123
	v_mov_b32_e32 v135, v123
	v_add_f32_e64 v166, v134, v150
	v_add_f32_e64 v167, v135, v151
	v_mul_f32_e32 v112, v118, v167
	v_fma_f32 v123, -v119, v166, v112
	v_mul_f32_e32 v112, v119, v167
	v_fma_f32 v134, v118, v166, v112
	v_mov_b32_e32 v135, v123
	v_add_f32_e64 v154, v134, v136
	v_add_f32_e64 v155, v135, v137
	v_mul_f32_e64 v122, v118, v154
	v_mul_f32_e64 v123, v119, v154
	v_fma_f32 v134, v120, v155, v122
	v_fma_f32 v123, v121, v155, -v123
	v_mov_b32_e32 v135, v123
	v_add_f32_e64 v164, v134, v132
	v_add_f32_e64 v165, v135, v133
	v_mul_f32_e32 v112, v118, v165
	v_fma_f32 v123, -v119, v164, v112
	v_mul_f32_e32 v112, v119, v165
	v_fma_f32 v132, v118, v164, v112
	v_mov_b32_e32 v133, v123
	v_add_f32_e64 v142, v132, v130
	v_add_f32_e64 v143, v133, v131
	v_mul_f32_e64 v122, v118, v142
	v_mul_f32_e64 v123, v119, v142
	v_fma_f32 v130, v120, v143, v122
	v_fma_f32 v123, v121, v143, -v123
	v_mov_b32_e32 v131, v123
	v_add_f32_e64 v158, v130, v128
	v_add_f32_e64 v159, v131, v129
	v_mul_f32_e32 v112, v118, v159
	v_fma_f32 v123, -v119, v158, v112
	v_mul_f32_e32 v112, v119, v159
	v_fma_f32 v128, v118, v158, v112
	v_mov_b32_e32 v129, v123
	v_add_f32_e64 v152, v128, v126
	v_add_f32_e64 v153, v129, v127
	v_mul_f32_e32 v112, v118, v153
	v_fma_f32 v123, -v119, v152, v112
	v_mul_f32_e32 v112, v119, v153
	v_fma_f32 v126, v118, v152, v112
	v_mov_b32_e32 v127, v123
	v_add_f32_e64 v148, v126, v124
	v_add_f32_e64 v149, v127, v125
	v_mul_f32_e32 v112, v118, v149
	v_fma_f32 v123, -v119, v148, v112
	v_mul_f32_e32 v112, v119, v149
	v_fma_f32 v124, v118, v148, v112
	v_mov_b32_e32 v112, v32
	v_mov_b32_e32 v125, v123
	v_add_f32_e64 v122, v124, v46
	v_add_f32_e64 v123, v125, v47
	v_mul_f32_e32 v46, v118, v123
	v_fma_f32 v47, -v119, v122, v46
	v_mul_f32_e32 v46, v119, v123
	v_fma_f32 v124, v118, v122, v46
	v_mov_b32_e32 v125, v47
	v_add_f32_e64 v146, v124, v44
	v_add_f32_e64 v147, v125, v45
	v_mul_f32_e32 v44, v118, v147
	v_fma_f32 v45, -v119, v146, v44
	v_mul_f32_e32 v44, v119, v147
	v_fma_f32 v46, v118, v146, v44
	v_mov_b32_e32 v47, v45
	v_add_f32_e64 v134, v46, v42
	v_add_f32_e64 v135, v47, v43
	v_mul_f32_e32 v42, v118, v135
	v_fma_f32 v43, -v119, v134, v42
	v_mul_f32_e32 v42, v119, v135
	v_fma_f32 v44, v118, v134, v42
	v_mov_b32_e32 v45, v43
	v_add_f32_e64 v144, v44, v40
	v_add_f32_e64 v145, v45, v41
	v_mul_f32_e32 v40, v118, v145
	v_fma_f32 v41, -v119, v144, v40
	v_mul_f32_e32 v40, v119, v145
	v_fma_f32 v42, v118, v144, v40
	v_mov_b32_e32 v43, v41
	v_add_f32_e64 v140, v42, v38
	v_add_f32_e64 v141, v43, v39
	v_mul_f32_e32 v38, v118, v141
	v_fma_f32 v39, -v119, v140, v38
	v_mul_f32_e32 v38, v119, v141
	v_fma_f32 v40, v118, v140, v38
	v_mov_b32_e32 v41, v39
	v_add_f32_e64 v138, v40, v36
	v_add_f32_e64 v139, v41, v37
	v_mul_f32_e64 v36, v120, v138
	v_mul_f32_e64 v37, v121, v138
	v_fma_f32 v38, v118, v139, -v36
	v_fma_f32 v36, v118, v139, v36
	v_fma_f32 v37, v119, v139, v37
	v_mov_b32_e32 v39, v37
	v_add_f32_e64 v180, v38, v34
	v_add_f32_e64 v181, v39, v35
	v_mov_b32_e32 v168, v181
	v_mov_b32_e32 v176, v180
	v_mov_b32_e32 v32, v181
.LBB0_648:
	v_add_u32_e32 v34, s21, v200
	v_cvt_pk_bf16_f32 v33, v33, v112
	v_cvt_pk_bf16_f32 v35, v161, v160
	v_add_u32_e32 v36, 0x2800, v34
	ds_write2_b32 v36, v33, v35 offset1:68
	v_cvt_pk_bf16_f32 v33, v167, v166
	v_cvt_pk_bf16_f32 v35, v155, v154
	ds_write2_b32 v36, v33, v35 offset0:136 offset1:204
	v_cvt_pk_bf16_f32 v33, v165, v164
	v_cvt_pk_bf16_f32 v35, v143, v142
	v_add_u32_e32 v36, 0x2c00, v34
	ds_write2_b32 v36, v33, v35 offset0:16 offset1:84
	v_cvt_pk_bf16_f32 v33, v159, v158
	v_cvt_pk_bf16_f32 v35, v153, v152
	ds_write2_b32 v36, v33, v35 offset0:152 offset1:220
	v_cvt_pk_bf16_f32 v33, v149, v148
	v_cvt_pk_bf16_f32 v35, v123, v122
	v_add_u32_e32 v36, 0x3000, v34
	ds_write2_b32 v36, v33, v35 offset0:32 offset1:100
	v_cvt_pk_bf16_f32 v33, v147, v146
	v_cvt_pk_bf16_f32 v35, v135, v134
	ds_write2_b32 v36, v33, v35 offset0:168 offset1:236
	v_cvt_pk_bf16_f32 v33, v145, v144
	v_cvt_pk_bf16_f32 v35, v141, v140
	v_add_u32_e32 v34, 0x3400, v34
	ds_write2_b32 v34, v33, v35 offset0:48 offset1:116
	v_cvt_pk_bf16_f32 v33, v139, v138
	v_cvt_pk_bf16_f32 v35, v176, v168
	ds_write2_b32 v34, v33, v35 offset0:184 offset1:252
	v_add_u32_e32 v33, s22, v199
	ds_read_b128 v[34:37], v33
	ds_read_b128 v[38:41], v33 offset:5120
	ds_read_b128 v[136:139], v33 offset:16
	ds_read_b128 v[144:147], v33 offset:5136
	v_mul_f32_e64 v33, v119, v32
	v_mul_f32_e64 v32, v118, v32
	s_waitcnt lgkmcnt(3)
	v_lshlrev_b32_e32 v167, 16, v34
	v_fma_f32 v122, v120, v180, -v32
	v_fma_f32 v123, v121, v180, -v33
	v_fma_f32 v178, v120, v180, v32
	s_waitcnt lgkmcnt(2)
	v_lshlrev_b32_e32 v166, 16, v38
	v_and_b32_e32 v161, 0xffff0000, v34
	v_and_b32_e32 v160, 0xffff0000, v38
	v_lshlrev_b32_e32 v159, 16, v35
	v_lshlrev_b32_e32 v158, 16, v39
	v_and_b32_e32 v143, 0xffff0000, v35
	v_and_b32_e32 v142, 0xffff0000, v39
	v_lshlrev_b32_e32 v135, 16, v36
	v_lshlrev_b32_e32 v134, 16, v40
	v_and_b32_e32 v131, 0xffff0000, v36
	v_and_b32_e32 v130, 0xffff0000, v40
	v_lshlrev_b32_e32 v129, 16, v37
	v_lshlrev_b32_e32 v128, 16, v41
	v_and_b32_e32 v127, 0xffff0000, v37
	v_and_b32_e32 v126, 0xffff0000, v41
	s_waitcnt lgkmcnt(1)
	v_lshlrev_b32_e32 v125, 16, v136
	s_waitcnt lgkmcnt(0)
	v_lshlrev_b32_e32 v124, 16, v144
	v_and_b32_e32 v47, 0xffff0000, v136
	v_and_b32_e32 v46, 0xffff0000, v144
	v_lshlrev_b32_e32 v45, 16, v137
	v_lshlrev_b32_e32 v44, 16, v145
	v_and_b32_e32 v43, 0xffff0000, v137
	v_and_b32_e32 v42, 0xffff0000, v145
	v_lshlrev_b32_e32 v41, 16, v138
	v_lshlrev_b32_e32 v40, 16, v146
	v_and_b32_e32 v39, 0xffff0000, v138
	v_and_b32_e32 v38, 0xffff0000, v146
	v_lshlrev_b32_e32 v37, 16, v139
	v_lshlrev_b32_e32 v36, 16, v147
	v_and_b32_e32 v35, 0xffff0000, v139
	v_and_b32_e32 v34, 0xffff0000, v147
	v_mov_b32_e32 v179, v123
	s_and_b64 vcc, exec, s[4:5]
	s_mov_b64 s[4:5], -1
	s_cbranch_vccnz .LBB0_650
	v_add_f32_e64 v150, v178, v34
	v_add_f32_e64 v151, v179, v35
	s_mov_b64 s[4:5], 0
	v_mul_f32_e64 v32, v118, v150
	v_mul_f32_e64 v33, v119, v150
	v_fma_f32 v122, v120, v151, v32
	v_fma_f32 v33, v121, v151, -v33
	v_mov_b32_e32 v123, v33
	v_add_f32_e64 v136, v122, v36
	v_add_f32_e64 v137, v123, v37
	v_mul_f32_e32 v32, v118, v137
	v_fma_f32 v33, -v119, v136, v32
	v_mul_f32_e32 v32, v119, v137
	v_fma_f32 v122, v118, v136, v32
	v_mov_b32_e32 v123, v33
	v_add_f32_e64 v138, v122, v38
	v_add_f32_e64 v139, v123, v39
	v_mul_f32_e64 v32, v118, v138
	v_mul_f32_e64 v33, v119, v138
	v_fma_f32 v122, v120, v139, v32
	v_fma_f32 v33, v121, v139, -v33
	v_mov_b32_e32 v123, v33
	v_add_f32_e64 v144, v122, v40
	v_add_f32_e64 v145, v123, v41
	v_mul_f32_e32 v32, v118, v145
	v_fma_f32 v33, -v119, v144, v32
	v_mul_f32_e32 v32, v119, v145
	v_fma_f32 v122, v118, v144, v32
	v_mov_b32_e32 v123, v33
	v_add_f32_e64 v132, v122, v42
	v_add_f32_e64 v133, v123, v43
	v_mul_f32_e64 v32, v118, v132
	v_mul_f32_e64 v33, v119, v132
	v_fma_f32 v122, v120, v133, v32
	v_fma_f32 v33, v121, v133, -v33
	v_mov_b32_e32 v123, v33
	v_add_f32_e64 v146, v122, v44
	v_add_f32_e64 v147, v123, v45
	v_mul_f32_e32 v32, v118, v147
	v_fma_f32 v33, -v119, v146, v32
	v_mul_f32_e32 v32, v119, v147
	v_fma_f32 v122, v118, v146, v32
	v_mov_b32_e32 v123, v33
	v_add_f32_e64 v32, v122, v46
	v_add_f32_e64 v33, v123, v47
	v_mul_f32_e64 v122, v118, v32
	v_mul_f32_e64 v123, v119, v32
	v_fma_f32 v140, v120, v33, v122
	v_fma_f32 v123, v121, v33, -v123
	v_mov_b32_e32 v141, v123
	v_add_f32_e64 v148, v140, v124
	v_add_f32_e64 v149, v141, v125
	v_mul_f32_e32 v112, v118, v149
	v_fma_f32 v123, -v119, v148, v112
	v_mul_f32_e32 v112, v119, v149
	v_fma_f32 v140, v118, v148, v112
	v_mov_b32_e32 v141, v123
	v_add_f32_e64 v152, v140, v126
	v_add_f32_e64 v153, v141, v127
	v_mul_f32_e32 v112, v118, v153
	v_fma_f32 v123, -v119, v152, v112
	v_mul_f32_e32 v112, v119, v153
	v_fma_f32 v140, v118, v152, v112
	v_mov_b32_e32 v141, v123
	v_add_f32_e64 v156, v140, v128
	v_add_f32_e64 v157, v141, v129
	v_mul_f32_e32 v112, v118, v157
	v_fma_f32 v123, -v119, v156, v112
	v_mul_f32_e32 v112, v119, v157
	v_fma_f32 v140, v118, v156, v112
	v_mov_b32_e32 v141, v123
	v_add_f32_e64 v140, v140, v130
	v_add_f32_e64 v141, v141, v131
	v_mul_f32_e32 v112, v118, v141
	v_fma_f32 v123, -v119, v140, v112
	v_mul_f32_e32 v112, v119, v141
	v_fma_f32 v154, v118, v140, v112
	v_mov_b32_e32 v155, v123
	v_add_f32_e64 v168, v154, v134
	v_add_f32_e64 v169, v155, v135
	v_mul_f32_e32 v112, v118, v169
	v_fma_f32 v123, -v119, v168, v112
	v_mul_f32_e32 v112, v119, v169
	v_fma_f32 v154, v118, v168, v112
	v_mov_b32_e32 v155, v123
	v_add_f32_e64 v154, v154, v142
	v_add_f32_e64 v155, v155, v143
	v_mul_f32_e32 v112, v118, v155
	v_fma_f32 v123, -v119, v154, v112
	v_mul_f32_e32 v112, v119, v155
	v_fma_f32 v162, v118, v154, v112
	v_mov_b32_e32 v163, v123
	v_add_f32_e64 v176, v162, v158
	v_add_f32_e64 v177, v163, v159
	v_mul_f32_e32 v112, v118, v177
	v_fma_f32 v123, -v119, v176, v112
	v_mul_f32_e32 v112, v119, v177
	v_fma_f32 v162, v118, v176, v112
	v_mov_b32_e32 v163, v123
	v_add_f32_e64 v162, v162, v160
	v_add_f32_e64 v163, v163, v161
	v_mul_f32_e32 v112, v118, v163
	v_fma_f32 v123, -v119, v162, v112
	v_mul_f32_e32 v112, v119, v163
	v_fma_f32 v164, v118, v162, v112
	v_mov_b32_e32 v165, v123
	v_add_f32_e64 v164, v164, v166
	v_add_f32_e64 v165, v165, v167
	v_mov_b32_e32 v112, v165
	v_mov_b32_e32 v122, v164
.LBB0_650:
	s_andn2_b64 vcc, exec, s[4:5]
	s_cbranch_vccnz .LBB0_643
	v_add_f32_e64 v164, v178, v166
	v_add_f32_e64 v165, v179, v167
	v_mul_f32_e32 v32, v118, v165
	v_fma_f32 v33, -v119, v164, v32
	v_mul_f32_e32 v32, v119, v165
	v_fma_f32 v122, v118, v164, v32
	v_mov_b32_e32 v123, v33
	v_add_f32_e64 v162, v122, v160
	v_add_f32_e64 v163, v123, v161
	v_mul_f32_e64 v32, v118, v162
	v_mul_f32_e64 v33, v119, v162
	v_fma_f32 v122, v120, v163, v32
	v_fma_f32 v33, v121, v163, -v33
	v_mov_b32_e32 v123, v33
	v_add_f32_e64 v176, v122, v158
	v_add_f32_e64 v177, v123, v159
	v_mul_f32_e32 v32, v118, v177
	v_fma_f32 v33, -v119, v176, v32
	v_mul_f32_e32 v32, v119, v177
	v_fma_f32 v122, v118, v176, v32
	v_mov_b32_e32 v123, v33
	v_add_f32_e64 v154, v122, v142
	v_add_f32_e64 v155, v123, v143
	v_mul_f32_e64 v32, v118, v154
	v_mul_f32_e64 v33, v119, v154
	v_fma_f32 v122, v120, v155, v32
	v_fma_f32 v33, v121, v155, -v33
	v_mov_b32_e32 v123, v33
	v_add_f32_e64 v168, v122, v134
	v_add_f32_e64 v169, v123, v135
	v_mul_f32_e32 v32, v118, v169
	v_fma_f32 v33, -v119, v168, v32
	v_mul_f32_e32 v32, v119, v169
	v_fma_f32 v122, v118, v168, v32
	v_mov_b32_e32 v123, v33
	v_add_f32_e64 v140, v122, v130
	v_add_f32_e64 v141, v123, v131
	v_mul_f32_e64 v32, v118, v140
	v_mul_f32_e64 v33, v119, v140
	v_fma_f32 v122, v120, v141, v32
	v_fma_f32 v33, v121, v141, -v33
	v_mov_b32_e32 v123, v33
	v_add_f32_e64 v156, v122, v128
	v_add_f32_e64 v157, v123, v129
	v_mul_f32_e32 v32, v118, v157
	v_fma_f32 v33, -v119, v156, v32
	v_mul_f32_e32 v32, v119, v157
	v_fma_f32 v122, v118, v156, v32
	v_mov_b32_e32 v123, v33
	v_add_f32_e64 v152, v122, v126
	v_add_f32_e64 v153, v123, v127
	v_mul_f32_e32 v32, v118, v153
	v_fma_f32 v33, -v119, v152, v32
	v_mul_f32_e32 v32, v119, v153
	v_fma_f32 v122, v118, v152, v32
	v_mov_b32_e32 v123, v33
	v_add_f32_e64 v148, v122, v124
	v_add_f32_e64 v149, v123, v125
	v_mul_f32_e32 v32, v118, v149
	v_fma_f32 v33, -v119, v148, v32
	v_mul_f32_e32 v32, v119, v149
	v_fma_f32 v122, v118, v148, v32
	v_mov_b32_e32 v123, v33
	v_add_f32_e64 v32, v122, v46
	v_add_f32_e64 v33, v123, v47
	v_mul_f32_e32 v46, v118, v33
	v_fma_f32 v47, -v119, v32, v46
	v_mul_f32_e32 v46, v119, v33
	v_fma_f32 v122, v118, v32, v46
	v_mov_b32_e32 v123, v47
	v_add_f32_e64 v146, v122, v44
	v_add_f32_e64 v147, v123, v45
	v_mul_f32_e32 v44, v118, v147
	v_fma_f32 v45, -v119, v146, v44
	v_mul_f32_e32 v44, v119, v147
	v_fma_f32 v46, v118, v146, v44
	v_mov_b32_e32 v47, v45
	v_add_f32_e64 v132, v46, v42
	v_add_f32_e64 v133, v47, v43
	v_mul_f32_e32 v42, v118, v133
	v_fma_f32 v43, -v119, v132, v42
	v_mul_f32_e32 v42, v119, v133
	v_fma_f32 v44, v118, v132, v42
	v_mov_b32_e32 v45, v43
	v_add_f32_e64 v144, v44, v40
	v_add_f32_e64 v145, v45, v41
	v_mul_f32_e32 v40, v118, v145
	v_fma_f32 v41, -v119, v144, v40
	v_mul_f32_e32 v40, v119, v145
	v_fma_f32 v42, v118, v144, v40
	v_mov_b32_e32 v43, v41
	v_add_f32_e64 v138, v42, v38
	v_add_f32_e64 v139, v43, v39
	v_mul_f32_e32 v38, v118, v139
	v_fma_f32 v39, -v119, v138, v38
	v_mul_f32_e32 v38, v119, v139
	v_fma_f32 v40, v118, v138, v38
	v_mov_b32_e32 v41, v39
	v_add_f32_e64 v136, v40, v36
	v_add_f32_e64 v137, v41, v37
	v_mul_f32_e64 v36, v118, v136
	v_mul_f32_e64 v37, v119, v136
	v_fma_f32 v38, v120, v136, -v36
	v_fma_f32 v39, v121, v137, -v37
	v_fma_f32 v36, v120, v137, v36
	v_mov_b32_e32 v37, v39
	v_add_f32_e64 v122, v36, v34
	v_add_f32_e64 v123, v37, v35
	v_mov_b32_e32 v150, v122
	v_mov_b32_e32 v112, v123
	v_mov_b32_e32 v151, v123
	s_branch .LBB0_643
